# v11 + next-tile index: shift/mask fast path when group size is 4 (original division kept as fallback); relu^2 epilogue canonicalising v_max removed
# baseline (speedup 1.0000x reference)
.LBB0_172:
	s_ashr_i32 s0, s10, 3
	s_add_i32 s0, s34, s0
	s_abs_i32 s10, s0
	s_mul_hi_u32 s11, s10, s37
	s_mul_i32 s34, s11, s13
	s_ashr_i32 s1, s0, 31
	s_sub_i32 s10, s10, s34
	s_xor_b32 s1, s1, s12
	s_add_i32 s34, s11, 1
	s_sub_i32 s35, s10, s13
	s_cmp_ge_u32 s10, s13
	s_cselect_b32 s11, s34, s11
	s_cselect_b32 s10, s35, s10
	s_add_i32 s34, s11, 1
	s_cmp_ge_u32 s10, s13
	s_cselect_b32 s10, s34, s11
	s_xor_b32 s10, s10, s1
	s_sub_i32 s1, s10, s1
	s_lshl_b32 s10, s1, 2
	s_sub_i32 s11, s51, s10
	s_min_i32 s11, s11, 4
	s_mul_i32 s1, s1, s9
	s_sub_i32 s0, s0, s1
	s_cmp_eq_u32 s11, 4
	s_cbranch_scc0 .Lgsz_slow
	s_lshr_b32 s40, s0, 2
	s_and_b32 s0, s0, 3
	s_branch .Lgsz_done
.Lgsz_slow:
	s_abs_i32 s34, s11
	v_cvt_f32_u32_e32 v2, s34
	s_sub_i32 s40, 0, s34
	v_rcp_iflag_f32_e32 v2, v2
	s_abs_i32 s35, s0
	s_xor_b32 s1, s0, s11
	s_ashr_i32 s1, s1, 31
	v_mul_f32_e32 v2, 0x4f7ffffe, v2
	v_cvt_u32_f32_e32 v2, v2
	s_nop 0
	v_readfirstlane_b32 s41, v2
	s_mul_i32 s40, s40, s41
	s_mul_hi_u32 s40, s41, s40
	s_add_i32 s41, s41, s40
	s_mul_hi_u32 s40, s35, s41
	s_mul_i32 s41, s40, s34
	s_sub_i32 s35, s35, s41
	s_add_i32 s41, s40, 1
	s_sub_i32 s81, s35, s34
	s_cmp_ge_u32 s35, s34
	s_cselect_b32 s40, s41, s40
	s_cselect_b32 s35, s81, s35
	s_add_i32 s41, s40, 1
	s_cmp_ge_u32 s35, s34
	s_cselect_b32 s34, s41, s40
	s_xor_b32 s34, s34, s1
	s_sub_i32 s40, s34, s1
	s_mul_i32 s1, s40, s11
	s_sub_i32 s0, s0, s1
.Lgsz_done:
	s_abs_i32 s1, s40
	s_mul_hi_u32 s11, s1, s96
	s_mul_i32 s34, s11, s62
	s_sub_i32 s1, s1, s34
	s_add_i32 s10, s0, s10
	s_ashr_i32 s0, s40, 31
	s_add_i32 s34, s11, 1
	s_sub_i32 s35, s1, s62
	s_cmp_ge_u32 s1, s62
	s_cselect_b32 s11, s34, s11
	s_cselect_b32 s1, s35, s1
	s_add_i32 s34, s11, 1
	s_cmp_ge_u32 s1, s62
	s_cselect_b32 s1, s34, s11
	s_xor_b32 s1, s1, s0
	s_sub_i32 s0, s1, s0
	s_mul_hi_i32 s35, s50, s0
	s_mul_i32 s34, s50, s0
	s_and_b64 s[0:1], s[76:77], exec
	s_cselect_b32 s81, s10, s40
	s_cselect_b32 s97, s40, s10
